# scan: next-chunk u rows loaded as 4 x dwordx4 per lane + v_permlane32_swap exchange (half the uncoalesced requests), vmcnt recounted
# speedup vs baseline: 1.0071x; 1.0071x over previous
; #define G_LOAD(ST, IT) do { const size_t o16 = (size_t)(IT) * 16384; \
;     _Pragma("unroll") for (int k = 0; k < 4; ++k) { ST[k] = *(const u32x4*)(gw + o16 + (tid + 256 * k) * 16); ST[4 + k] = *(const u32x4*)(gkt + o16 + (tid + 256 * k) * 16); } } while (0)
; #define U_LOAD(IT) do { _Pragma("unroll") for (int k = 0; k < 8; ++k) uc[k] = *(const uint2*)(gut + (size_t)(IT) * 8192 + dv * 64 + 32 * (k >> 2) + 8 * (k & 3) + 4 * hi); } while (0)
; __device__ __forceinline__ void gdn_scan_item(const Params& p, int bh, char* smem) {
;     ...
;   u32x4* sbg = (u32x4*)(p.ws + OFF_PROJ); u32x4* vbg = (u32x4*)(p.ws + OFF_PROJ + (size_t)2048 * 32768);
;   f32x16 S[4];
; #pragma unroll
;   for (int T = 0; T < 4; ++T)
; #pragma unroll
;     for (int r = 0; r < 16; ++r) S[T][r] = 0.f;
;   u32x4 sa[8], sb_[8]; uint2 uc[8];
;   const int dv = wid * 32 + r32;
;     ...
;   float sd_cur = gsd[bh * 128];
;   G_LOAD(sa, bh * 128); U_LOAD(bh * 128); G_WRITE(sa);
;   G_LOAD(sb_, bh * 128 + 1);
;   __syncthreads();
.LBB0_1198:
	s_and_b64 vcc, exec, s[0:1]
	s_waitcnt lgkmcnt(0)
	v_readlane_b32 s18, v244, 0
	v_readlane_b32 s19, v244, 1
	s_cbranch_vccz .LBB0_1209
	s_add_u32 s2, s76, 0x161b4000
	s_addc_u32 s3, s77, 0
	s_add_u32 s4, s76, 0x1c1b4000
	s_addc_u32 s5, s77, 0
	s_add_u32 s14, s76, 0x1a1b4000
	s_addc_u32 s15, s77, 0
	s_lshl_b32 s0, s18, 7
	s_ashr_i32 s1, s0, 31
	s_lshl_b64 s[6:7], s[0:1], 2
	s_add_u32 s6, s76, s6
	s_addc_u32 s7, s77, s7
	s_lshl_b64 s[8:9], s[0:1], 14
	v_mov_b32_e32 v4, v198
	s_add_u32 s10, s2, s8
	s_addc_u32 s11, s3, s9
	v_lshlrev_b32_e32 v160, 4, v4
	s_add_u32 s12, s14, s8
	v_ashrrev_i32_e32 v161, 31, v160
	s_addc_u32 s13, s15, s9
	v_lshl_add_u64 v[0:1], s[10:11], 0, v[160:161]
	v_add_u32_e32 v162, 0x1000, v160
	global_load_dwordx4 v[96:99], v[0:1], off
	v_lshl_add_u64 v[0:1], s[12:13], 0, v[160:161]
	v_ashrrev_i32_e32 v163, 31, v162
	v_add_u32_e32 v164, 0x2000, v160
	v_lshl_add_u64 v[2:3], s[10:11], 0, v[162:163]
	global_load_dwordx4 v[100:103], v[0:1], off
	global_load_dwordx4 v[104:107], v[2:3], off
	v_lshl_add_u64 v[0:1], s[12:13], 0, v[162:163]
	v_ashrrev_i32_e32 v165, 31, v164
	v_add_u32_e32 v166, 0x3000, v160
	v_lshl_add_u64 v[2:3], s[10:11], 0, v[164:165]
	global_load_dwordx4 v[108:111], v[0:1], off
	global_load_dwordx4 v[112:115], v[2:3], off
	v_lshl_add_u64 v[0:1], s[12:13], 0, v[164:165]
	v_ashrrev_i32_e32 v167, 31, v166
	global_load_dwordx4 v[116:119], v[0:1], off
	v_lshl_add_u64 v[0:1], s[10:11], 0, v[166:167]
	global_load_dwordx4 v[120:123], v[0:1], off
	v_lshl_add_u64 v[0:1], s[12:13], 0, v[166:167]
	global_load_dwordx4 v[124:127], v[0:1], off
	v_mov_b32_e32 v0, 0x1f1b4000
	v_and_b32_e32 v7, 31, v4
	global_load_dword v170, v0, s[6:7]
	s_movk_i32 s12, 0x108
	v_ashrrev_i32_e32 v6, 6, v4
	v_lshrrev_b32_e32 v0, 2, v4
	v_ashrrev_i32_e32 v1, 4, v4
	v_lshlrev_b32_e32 v9, 6, v7
	s_movk_i32 s13, 0x88
	v_lshrrev_b32_e32 v2, 3, v4
	v_add_u32_e32 v3, 0x100, v4
	v_and_b32_e32 v168, 8, v0
	v_and_b32_e32 v10, 0xf0, v160
	v_mul_lo_u32 v1, v1, s12
	v_lshl_or_b32 v0, v6, 11, v9
	s_movk_i32 s16, 0x4200
	v_and_b32_e32 v11, 0x70, v160
	v_mul_lo_u32 v2, v2, s13
	v_ashrrev_i32_e32 v12, 4, v3
	v_lshrrev_b32_e32 v3, 3, v3
	v_add_u32_e32 v171, v10, v1
	v_ashrrev_i32_e32 v1, 31, v0
	s_add_u32 s10, s4, s8
	v_add3_u32 v199, v11, v2, s16
	v_mul_lo_u32 v2, v12, s12
	v_mul_lo_u32 v3, v3, s13
	v_lshlrev_b64 v[0:1], 1, v[0:1]
	s_addc_u32 s11, s5, s9
	v_mov_b32_e32 v169, 0
	v_add_u32_e32 v200, v10, v2
	v_add3_u32 v201, v11, v3, s16
	v_lshl_add_u64 v[2:3], s[10:11], 0, v[0:1]
	v_lshl_add_u64 v[2:3], v[2:3], 0, v[168:169]
	s_or_b32 s10, s0, 1
	v_add_u32_e32 v5, 0x200, v4
	v_bfe_u32 v254, v198, 5, 1
	v_mul_i32_i24_e32 v254, 0xffffffe8, v254
	v_add_u32_e32 v254, 16, v254
	v_ashrrev_i32_e32 v255, 31, v254
	v_lshl_add_u64 v[248:249], v[2:3], 0, v[254:255]
	global_load_dwordx4 v[194:197], v[248:249], off
	global_load_dwordx4 v[190:193], v[248:249], off offset:32
	global_load_dwordx4 v[250:253], v[248:249], off offset:64
	global_load_dwordx4 v[172:175], v[248:249], off offset:96
	v_add_u32_e32 v2, 0x300, v4
	s_ashr_i32 s11, s10, 31
	v_ashrrev_i32_e32 v13, 4, v5
	v_ashrrev_i32_e32 v3, 4, v2
	s_lshl_b64 s[10:11], s[10:11], 14
	v_lshrrev_b32_e32 v5, 3, v5
	v_mul_lo_u32 v9, v13, s12
	v_mul_lo_u32 v3, v3, s12
	v_lshrrev_b32_e32 v2, 3, v2
	s_add_u32 s12, s2, s10
	v_mul_lo_u32 v5, v5, s13
	v_mul_lo_u32 v2, v2, s13
	s_addc_u32 s13, s3, s11
	v_add3_u32 v203, v11, v5, s16
	v_add_u32_e32 v204, v10, v3
	v_add3_u32 v205, v11, v2, s16
	s_add_u32 s10, s14, s10
	v_add_u32_e32 v202, v10, v9
	s_addc_u32 s11, s15, s11
	v_lshl_add_u64 v[2:3], s[12:13], 0, v[160:161]
	s_waitcnt vmcnt(0)
; #define G_LOAD(ST, IT) do { const size_t o16 = (size_t)(IT) * 16384; \
;     _Pragma("unroll") for (int k = 0; k < 4; ++k) { ST[k] = *(const u32x4*)(gw + o16 + (tid + 256 * k) * 16); ST[4 + k] = *(const u32x4*)(gkt + o16 + (tid + 256 * k) * 16); } } while (0)
; #define U_LOAD(IT) do { _Pragma("unroll") for (int k = 0; k < 8; ++k) uc[k] = *(const uint2*)(gut + (size_t)(IT) * 8192 + dv * 64 + 32 * (k >> 2) + 8 * (k & 3) + 4 * hi); } while (0)
; __device__ __forceinline__ void gdn_scan_item(const Params& p, int bh, char* smem) {
;     ...
;   f32x16 S[4];
; #pragma unroll
;   for (int T = 0; T < 4; ++T)
; #pragma unroll
;     for (int r = 0; r < 16; ++r) S[T][r] = 0.f;
;   u32x4 sa[8], sb_[8]; uint2 uc[8];
;   const int dv = wid * 32 + r32;
;     ...
;   float sd_cur = gsd[bh * 128];
;   G_LOAD(sa, bh * 128); U_LOAD(bh * 128); G_WRITE(sa);
;   G_LOAD(sb_, bh * 128 + 1);
;   __syncthreads();
	ds_write2_b64 v171, v[96:97], v[98:99] offset1:1
	ds_write2_b64 v199, v[100:101], v[102:103] offset1:1
	ds_write2_b64 v200, v[104:105], v[106:107] offset1:1
	ds_write2_b64 v201, v[108:109], v[110:111] offset1:1
	ds_write2_b64 v202, v[112:113], v[114:115] offset1:1
	v_and_b32_e32 v8, 63, v4
	v_lshl_add_u64 v[4:5], s[10:11], 0, v[160:161]
	ds_write2_b64 v203, v[116:117], v[118:119] offset1:1
	s_add_u32 s6, s6, 0x1f1b4004
	ds_write2_b64 v204, v[120:121], v[122:123] offset1:1
	s_movk_i32 s1, 0x1000
	ds_write2_b64 v205, v[124:125], v[126:127] offset1:1
	global_load_dwordx4 v[128:131], v[2:3], off
	global_load_dwordx4 v[132:135], v[4:5], off
	v_lshl_add_u64 v[2:3], s[12:13], 0, v[162:163]
	v_lshl_add_u64 v[4:5], s[10:11], 0, v[162:163]
	global_load_dwordx4 v[136:139], v[2:3], off
	global_load_dwordx4 v[140:143], v[4:5], off
	v_lshl_add_u64 v[2:3], s[12:13], 0, v[164:165]
	v_lshl_add_u64 v[4:5], s[10:11], 0, v[164:165]
	global_load_dwordx4 v[144:147], v[2:3], off
	global_load_dwordx4 v[148:151], v[4:5], off
	v_lshl_add_u64 v[2:3], s[12:13], 0, v[166:167]
	v_lshl_add_u64 v[4:5], s[10:11], 0, v[166:167]
	global_load_dwordx4 v[152:155], v[2:3], off
	global_load_dwordx4 v[156:159], v[4:5], off
	v_lshlrev_b32_e32 v2, 4, v8
	v_mov_b32_e32 v3, v169
	v_lshl_add_u64 v[2:3], s[76:77], 0, v[2:3]
	s_mov_b64 s[10:11], 0xe1b4000
	v_lshl_add_u64 v[178:179], v[2:3], 0, s[10:11]
	s_mov_b64 s[10:11], 0x121b4000
	v_lshl_add_u64 v[180:181], v[2:3], 0, s[10:11]
	v_lshl_add_u64 v[2:3], s[4:5], 0, v[0:1]
	v_lshl_add_u64 v[182:183], v[2:3], 0, v[168:169]
	v_or_b32_e32 v2, s8, v168
	v_mov_b32_e32 v3, s9
	v_lshl_add_u64 v[0:1], v[2:3], 0, v[0:1]
	v_mul_u32_u24_e32 v4, 0x108, v7
	v_mul_u32_u24_e32 v5, 0x88, v7
	v_lshl_add_u64 v[0:1], s[76:77], 0, v[0:1]
	s_mov_b64 s[4:5], 0x1c1b8040
	v_lshl_add_u32 v184, s18, 9, v6
	s_addc_u32 s7, s7, 0
	v_lshl_add_u64 v[188:189], v[0:1], 0, s[4:5]
	s_mov_b32 s16, 0
	s_mov_b64 s[8:9], 0x8000
	v_add_u32_e32 v206, v4, v168
	v_add_u32_e32 v207, v168, v5
	v_mov_b32_e32 v0, 0
	v_mov_b32_e32 v1, v169
	v_mov_b32_e32 v2, v169
	v_mov_b32_e32 v3, v169
	v_mov_b32_e32 v4, v169
	v_mov_b32_e32 v5, v169
	v_mov_b32_e32 v6, v169
	v_mov_b32_e32 v7, v169
	v_mov_b32_e32 v8, v169
	v_mov_b32_e32 v9, v169
	v_mov_b32_e32 v10, v169
	v_mov_b32_e32 v11, v169
	v_mov_b32_e32 v12, v169
	v_mov_b32_e32 v13, v169
	v_mov_b32_e32 v14, v169
	v_mov_b32_e32 v15, v169
	v_mov_b32_e32 v16, 0
	v_mov_b32_e32 v17, v169
	v_mov_b32_e32 v18, v169
	v_mov_b32_e32 v19, v169
	v_mov_b32_e32 v20, v169
	v_mov_b32_e32 v21, v169
	v_mov_b32_e32 v22, v169
	v_mov_b32_e32 v23, v169
	v_mov_b32_e32 v24, v169
	v_mov_b32_e32 v25, v169
	v_mov_b32_e32 v26, v169
	v_mov_b32_e32 v27, v169
	v_mov_b32_e32 v28, v169
	v_mov_b32_e32 v29, v169
	v_mov_b32_e32 v30, v169
	v_mov_b32_e32 v31, v169
	v_mov_b32_e32 v32, 0
	v_mov_b32_e32 v33, v169
	v_mov_b32_e32 v34, v169
	v_mov_b32_e32 v35, v169
	v_mov_b32_e32 v36, v169
	v_mov_b32_e32 v37, v169
	v_mov_b32_e32 v38, v169
	v_mov_b32_e32 v39, v169
	v_mov_b32_e32 v40, v169
	v_mov_b32_e32 v41, v169
	v_mov_b32_e32 v42, v169
	v_mov_b32_e32 v43, v169
	v_mov_b32_e32 v44, v169
	v_mov_b32_e32 v45, v169
	v_mov_b32_e32 v46, v169
	v_mov_b32_e32 v47, v169
	v_mov_b32_e32 v48, 0
	v_mov_b32_e32 v49, v169
	v_mov_b32_e32 v50, v169
	v_mov_b32_e32 v51, v169
	v_mov_b32_e32 v52, v169
	v_mov_b32_e32 v53, v169
	v_mov_b32_e32 v54, v169
	v_mov_b32_e32 v55, v169
	v_mov_b32_e32 v56, v169
	v_mov_b32_e32 v57, v169
	v_mov_b32_e32 v58, v169
	v_mov_b32_e32 v59, v169
	v_mov_b32_e32 v60, v169
	v_mov_b32_e32 v61, v169
	v_mov_b32_e32 v62, v169
	v_mov_b32_e32 v63, v169
	s_waitcnt lgkmcnt(0)
	s_barrier
	s_branch .LBB0_1201

.LBB0_1203:
	v_add_u32_e32 v208, 0x2000, v206
	ds_read2_b64 v[64:67], v206 offset1:2
	ds_read2_b64 v[210:213], v206 offset0:4 offset1:6
	ds_read2_b64 v[68:71], v208 offset0:32 offset1:34
	ds_read2_b64 v[214:217], v208 offset0:36 offset1:38
	v_ashrrev_i32_e32 v185, 31, v184
	v_lshlrev_b64 v[226:227], 13, v[184:185]
	v_cvt_pk_bf16_f32 v218, v0, v1
	v_cvt_pk_bf16_f32 v219, v2, v3
	v_cvt_pk_bf16_f32 v220, v4, v5
	v_cvt_pk_bf16_f32 v221, v6, v7
	v_lshl_add_u64 v[234:235], v[178:179], 0, v[226:227]
	v_cvt_pk_bf16_f32 v222, v8, v9
	s_waitcnt lgkmcnt(3)
	v_mfma_f32_32x32x16_bf16 v[80:95], v[64:67], v[218:221], 0
	v_cvt_pk_bf16_f32 v223, v10, v11
	v_cvt_pk_bf16_f32 v224, v12, v13
	v_cvt_pk_bf16_f32 v225, v14, v15
	global_store_dwordx4 v[234:235], v[218:221], off
	global_store_dwordx4 v[234:235], v[222:225], off offset:1024
	s_waitcnt lgkmcnt(1)
	v_mfma_f32_32x32x16_bf16 v[64:79], v[68:71], v[218:221], 0
	v_mfma_f32_32x32x16_bf16 v[80:95], v[210:213], v[222:225], v[80:95]
	ds_read2_b64 v[210:213], v206 offset0:8 offset1:10
	ds_read2_b64 v[218:221], v206 offset0:12 offset1:14
	ds_read2_b64 v[226:229], v208 offset0:40 offset1:42
	ds_read2_b64 v[230:233], v208 offset0:44 offset1:46
	s_waitcnt lgkmcnt(4)
	v_mfma_f32_32x32x16_bf16 v[64:79], v[214:217], v[222:225], v[64:79]
	v_cvt_pk_bf16_f32 v214, v16, v17
	v_cvt_pk_bf16_f32 v215, v18, v19
	v_cvt_pk_bf16_f32 v216, v20, v21
	v_cvt_pk_bf16_f32 v217, v22, v23
	s_waitcnt lgkmcnt(3)
	s_nop 0
	v_mfma_f32_32x32x16_bf16 v[80:95], v[210:213], v[214:217], v[80:95]
	v_cvt_pk_bf16_f32 v210, v24, v25
	v_cvt_pk_bf16_f32 v211, v26, v27
	v_cvt_pk_bf16_f32 v212, v28, v29
	v_cvt_pk_bf16_f32 v213, v30, v31
	global_store_dwordx4 v[234:235], v[214:217], off offset:2048
	global_store_dwordx4 v[234:235], v[210:213], off offset:3072
	s_waitcnt lgkmcnt(1)
	v_mfma_f32_32x32x16_bf16 v[64:79], v[226:229], v[214:217], v[64:79]
	v_mfma_f32_32x32x16_bf16 v[80:95], v[218:221], v[210:213], v[80:95]
	ds_read2_b64 v[214:217], v206 offset0:16 offset1:18
	ds_read2_b64 v[218:221], v206 offset0:20 offset1:22
	ds_read2_b64 v[222:225], v208 offset0:48 offset1:50
	ds_read2_b64 v[226:229], v208 offset0:52 offset1:54
	s_waitcnt lgkmcnt(4)
	v_mfma_f32_32x32x16_bf16 v[64:79], v[230:233], v[210:213], v[64:79]
	v_cvt_pk_bf16_f32 v210, v32, v33
	v_cvt_pk_bf16_f32 v211, v34, v35
	v_cvt_pk_bf16_f32 v212, v36, v37
	v_cvt_pk_bf16_f32 v213, v38, v39
	v_add_co_u32_e32 v234, vcc, s1, v234
	s_waitcnt lgkmcnt(3)
	v_mfma_f32_32x32x16_bf16 v[80:95], v[214:217], v[210:213], v[80:95]
	v_addc_co_u32_e32 v235, vcc, 0, v235, vcc
	v_cvt_pk_bf16_f32 v214, v40, v41
	v_cvt_pk_bf16_f32 v215, v42, v43
	v_cvt_pk_bf16_f32 v216, v44, v45
	v_cvt_pk_bf16_f32 v217, v46, v47
	global_store_dwordx4 v[234:235], v[210:213], off
	global_store_dwordx4 v[234:235], v[214:217], off offset:1024
	s_waitcnt lgkmcnt(1)
	v_mfma_f32_32x32x16_bf16 v[64:79], v[222:225], v[210:213], v[64:79]
	v_mfma_f32_32x32x16_bf16 v[80:95], v[218:221], v[214:217], v[80:95]
	ds_read2_b64 v[210:213], v206 offset0:24 offset1:26
	ds_read2_b64 v[218:221], v206 offset0:28 offset1:30
	ds_read2_b64 v[222:225], v208 offset0:56 offset1:58
	ds_read2_b64 v[230:233], v208 offset0:60 offset1:62
	s_waitcnt lgkmcnt(4)
	v_mfma_f32_32x32x16_bf16 v[64:79], v[226:229], v[214:217], v[64:79]
	v_cvt_pk_bf16_f32 v214, v48, v49
	v_cvt_pk_bf16_f32 v215, v50, v51
	v_cvt_pk_bf16_f32 v216, v52, v53
	v_cvt_pk_bf16_f32 v217, v54, v55
	v_cvt_pk_bf16_f32 v226, v56, v57
	v_cvt_pk_bf16_f32 v227, v58, v59
	s_waitcnt lgkmcnt(3)
	v_mfma_f32_32x32x16_bf16 v[80:95], v[210:213], v[214:217], v[80:95]
	v_cvt_pk_bf16_f32 v228, v60, v61
	v_cvt_pk_bf16_f32 v229, v62, v63
	s_waitcnt vmcnt(22)
	v_permlane32_swap_b32_e32 v194, v196
	v_permlane32_swap_b32_e32 v195, v197
	v_lshlrev_b32_e32 v212, 16, v196
	v_and_b32_e32 v213, 0xffff0000, v196
	v_lshlrev_b32_e32 v196, 16, v197
	v_and_b32_e32 v197, 0xffff0000, v197
	v_lshlrev_b64 v[210:211], 12, v[184:185]
	s_waitcnt lgkmcnt(1)
	v_mfma_f32_32x32x16_bf16 v[64:79], v[222:225], v[214:217], v[64:79]
	v_lshl_add_u64 v[210:211], v[180:181], 0, v[210:211]
	global_store_dwordx4 v[234:235], v[214:217], off offset:2048
	global_store_dwordx4 v[234:235], v[226:229], off offset:3072
	v_mfma_f32_32x32x16_bf16 v[80:95], v[218:221], v[226:229], v[80:95]
	s_waitcnt lgkmcnt(0)
	v_mfma_f32_32x32x16_bf16 v[64:79], v[230:233], v[226:229], v[64:79]
	s_nop 9
	v_add_f32_e64 v82, v196, -v82
	v_add_f32_e64 v83, v197, -v83
	s_waitcnt vmcnt(24)
	v_lshlrev_b32_e32 v196, 16, v194
	v_and_b32_e32 v197, 0xffff0000, v194
	v_pk_add_f32 v[196:197], v[196:197], v[84:85] neg_lo:[0,1] neg_hi:[0,1]
	v_lshlrev_b32_e32 v84, 16, v195
	v_and_b32_e32 v85, 0xffff0000, v195
	v_pk_add_f32 v[194:195], v[84:85], v[86:87] neg_lo:[0,1] neg_hi:[0,1]
	s_waitcnt vmcnt(23)
	v_permlane32_swap_b32_e32 v190, v192
	v_permlane32_swap_b32_e32 v191, v193
	v_lshlrev_b32_e32 v84, 16, v192
	v_and_b32_e32 v85, 0xffff0000, v192
	v_pk_add_f32 v[88:89], v[84:85], v[88:89] neg_lo:[0,1] neg_hi:[0,1]
	v_lshlrev_b32_e32 v84, 16, v193
	v_and_b32_e32 v85, 0xffff0000, v193
	v_pk_add_f32 v[90:91], v[84:85], v[90:91] neg_lo:[0,1] neg_hi:[0,1]
	s_waitcnt vmcnt(23)
	v_lshlrev_b32_e32 v84, 16, v190
	v_and_b32_e32 v85, 0xffff0000, v190
	v_pk_add_f32 v[80:81], v[212:213], v[80:81] neg_lo:[0,1] neg_hi:[0,1]
	v_pk_add_f32 v[92:93], v[84:85], v[92:93] neg_lo:[0,1] neg_hi:[0,1]
	v_lshlrev_b32_e32 v84, 16, v191
	v_sub_f32_e32 v94, v84, v94
	v_cvt_pk_bf16_f32 v84, v80, v81
	v_cvt_pk_bf16_f32 v80, v88, v89
	s_waitcnt vmcnt(22)
	v_permlane32_swap_b32_e32 v250, v252
	v_permlane32_swap_b32_e32 v251, v253
	v_mov_b32_e32 v176, v250
	v_mov_b32_e32 v177, v251
	v_mov_b32_e32 v186, v252
	v_mov_b32_e32 v187, v253
	v_lshlrev_b32_e32 v88, 16, v186
	v_and_b32_e32 v89, 0xffff0000, v186
	v_pk_add_f32 v[64:65], v[88:89], v[64:65] neg_lo:[0,1] neg_hi:[0,1]
	v_lshlrev_b32_e32 v88, 16, v187
	v_and_b32_e32 v89, 0xffff0000, v187
	v_pk_add_f32 v[66:67], v[88:89], v[66:67] neg_lo:[0,1] neg_hi:[0,1]
	s_waitcnt vmcnt(22)
	v_lshlrev_b32_e32 v88, 16, v176
	v_and_b32_e32 v89, 0xffff0000, v176
	v_pk_add_f32 v[88:89], v[88:89], v[68:69] neg_lo:[0,1] neg_hi:[0,1]
	v_lshlrev_b32_e32 v68, 16, v177
	v_and_b32_e32 v69, 0xffff0000, v177
	v_cvt_pk_bf16_f32 v81, v90, v91
	v_pk_add_f32 v[90:91], v[68:69], v[70:71] neg_lo:[0,1] neg_hi:[0,1]
	s_waitcnt vmcnt(21)
	v_permlane32_swap_b32_e32 v172, v174
	v_permlane32_swap_b32_e32 v173, v175
	v_lshlrev_b32_e32 v68, 16, v174
	v_and_b32_e32 v69, 0xffff0000, v174
	v_pk_add_f32 v[72:73], v[68:69], v[72:73] neg_lo:[0,1] neg_hi:[0,1]
	v_lshlrev_b32_e32 v68, 16, v175
	v_and_b32_e32 v69, 0xffff0000, v175
	v_pk_add_f32 v[74:75], v[68:69], v[74:75] neg_lo:[0,1] neg_hi:[0,1]
	s_waitcnt vmcnt(21)
	v_lshlrev_b32_e32 v68, 16, v172
	v_and_b32_e32 v69, 0xffff0000, v172
	v_and_b32_e32 v85, 0xffff0000, v191
	v_pk_add_f32 v[76:77], v[68:69], v[76:77] neg_lo:[0,1] neg_hi:[0,1]
	v_lshlrev_b32_e32 v68, 16, v173
	v_and_b32_e32 v69, 0xffff0000, v173
	v_sub_f32_e32 v95, v85, v95
	v_cvt_pk_bf16_f32 v85, v82, v83
	v_cvt_pk_bf16_f32 v86, v196, v197
	v_cvt_pk_bf16_f32 v87, v194, v195
	v_lshl_add_u64 v[248:249], v[188:189], 0, v[254:255]
	global_load_dwordx4 v[194:197], v[248:249], off offset:-64
	global_load_dwordx4 v[190:193], v[248:249], off offset:-32
	global_load_dwordx4 v[250:253], v[248:249], off
	global_load_dwordx4 v[172:175], v[248:249], off offset:32
	v_sub_f32_e32 v79, v69, v79
	v_sub_f32_e32 v78, v68, v78
	v_cvt_pk_bf16_f32 v68, v64, v65
	v_cvt_pk_bf16_f32 v69, v66, v67
	v_cvt_pk_bf16_f32 v70, v88, v89
	v_cvt_pk_bf16_f32 v71, v90, v91
	v_cvt_pk_bf16_f32 v82, v92, v93
	v_cvt_pk_bf16_f32 v83, v94, v95
	global_store_dwordx4 v[210:211], v[84:87], off
	global_store_dwordx4 v[210:211], v[80:83], off offset:1024
	v_cvt_pk_bf16_f32 v64, v72, v73
	v_cvt_pk_bf16_f32 v65, v74, v75
	v_cvt_pk_bf16_f32 v66, v76, v77
	v_cvt_pk_bf16_f32 v67, v78, v79
	global_store_dwordx4 v[210:211], v[68:71], off offset:2048
	global_store_dwordx4 v[210:211], v[64:67], off offset:3072
	v_add_u32_e32 v211, 0x4000, v207
	ds_read2_b64 v[72:75], v211 offset0:64 offset1:66
	ds_read2_b64 v[76:79], v211 offset0:68 offset1:70
	ds_read2_b64 v[88:91], v211 offset0:72 offset1:74
	ds_read2_b64 v[92:95], v211 offset0:76 offset1:78
	v_pk_mul_f32 v[14:15], v[14:15], v[170:171] op_sel_hi:[1,0]
	v_pk_mul_f32 v[12:13], v[12:13], v[170:171] op_sel_hi:[1,0]
	v_pk_mul_f32 v[10:11], v[10:11], v[170:171] op_sel_hi:[1,0]
	v_pk_mul_f32 v[8:9], v[8:9], v[170:171] op_sel_hi:[1,0]
	v_pk_mul_f32 v[6:7], v[6:7], v[170:171] op_sel_hi:[1,0]
	v_pk_mul_f32 v[4:5], v[4:5], v[170:171] op_sel_hi:[1,0]
	v_pk_mul_f32 v[2:3], v[2:3], v[170:171] op_sel_hi:[1,0]
	v_pk_mul_f32 v[0:1], v[0:1], v[170:171] op_sel_hi:[1,0]
	v_add_u32_e32 v210, 0x5000, v207
	s_waitcnt lgkmcnt(3)
	v_mfma_f32_32x32x16_bf16 v[0:15], v[72:75], v[84:87], v[0:15]
	s_waitcnt lgkmcnt(2)
	v_mfma_f32_32x32x16_bf16 v[0:15], v[76:79], v[80:83], v[0:15]
	s_waitcnt lgkmcnt(1)
	v_mfma_f32_32x32x16_bf16 v[0:15], v[88:91], v[68:71], v[0:15]
	ds_read2_b64 v[72:75], v210 offset0:96 offset1:98
	ds_read2_b64 v[76:79], v210 offset0:100 offset1:102
	ds_read2_b64 v[88:91], v210 offset0:104 offset1:106
	ds_read2_b64 v[212:215], v210 offset0:108 offset1:110
	s_waitcnt lgkmcnt(4)
	v_mfma_f32_32x32x16_bf16 v[0:15], v[92:95], v[64:67], v[0:15]
	v_mul_f32_e64 v30, v30, v170
	v_mul_f32_e64 v31, v31, v170
	v_mul_f32_e64 v28, v28, v170
	v_mul_f32_e64 v29, v29, v170
	v_mul_f32_e64 v26, v26, v170
	v_mul_f32_e64 v27, v27, v170
	v_pk_mul_f32 v[24:25], v[24:25], v[170:171] op_sel_hi:[1,0]
	v_pk_mul_f32 v[22:23], v[22:23], v[170:171] op_sel_hi:[1,0]
	v_pk_mul_f32 v[20:21], v[20:21], v[170:171] op_sel_hi:[1,0]
	v_pk_mul_f32 v[18:19], v[18:19], v[170:171] op_sel_hi:[1,0]
	v_pk_mul_f32 v[16:17], v[16:17], v[170:171] op_sel_hi:[1,0]
	v_add_u32_e32 v209, 0x6000, v207
	s_waitcnt lgkmcnt(3)
	v_mfma_f32_32x32x16_bf16 v[16:31], v[72:75], v[84:87], v[16:31]
	s_waitcnt lgkmcnt(2)
	v_mfma_f32_32x32x16_bf16 v[16:31], v[76:79], v[80:83], v[16:31]
	s_waitcnt lgkmcnt(1)
	v_mfma_f32_32x32x16_bf16 v[16:31], v[88:91], v[68:71], v[16:31]
	ds_read2_b64 v[72:75], v209 offset0:128 offset1:130
	ds_read2_b64 v[76:79], v209 offset0:132 offset1:134
	ds_read2_b64 v[88:91], v209 offset0:136 offset1:138
	ds_read2_b64 v[92:95], v209 offset0:140 offset1:142
	s_waitcnt lgkmcnt(4)
	v_mfma_f32_32x32x16_bf16 v[16:31], v[212:215], v[64:67], v[16:31]
	v_mul_f32_e64 v46, v46, v170
	v_mul_f32_e64 v47, v47, v170
	v_mul_f32_e64 v44, v44, v170
	v_mul_f32_e64 v45, v45, v170
	v_mul_f32_e64 v42, v42, v170
	v_mul_f32_e64 v43, v43, v170
	v_pk_mul_f32 v[40:41], v[40:41], v[170:171] op_sel_hi:[1,0]
	v_pk_mul_f32 v[38:39], v[38:39], v[170:171] op_sel_hi:[1,0]
	v_pk_mul_f32 v[36:37], v[36:37], v[170:171] op_sel_hi:[1,0]
	v_pk_mul_f32 v[34:35], v[34:35], v[170:171] op_sel_hi:[1,0]
	v_pk_mul_f32 v[32:33], v[32:33], v[170:171] op_sel_hi:[1,0]
	v_add_u32_e32 v185, 0x7000, v207
	s_waitcnt lgkmcnt(3)
	v_mfma_f32_32x32x16_bf16 v[32:47], v[72:75], v[84:87], v[32:47]
	s_waitcnt lgkmcnt(2)
	v_mfma_f32_32x32x16_bf16 v[32:47], v[76:79], v[80:83], v[32:47]
	s_waitcnt lgkmcnt(1)
	v_mfma_f32_32x32x16_bf16 v[32:47], v[88:91], v[68:71], v[32:47]
	ds_read2_b64 v[72:75], v185 offset0:160 offset1:162
	ds_read2_b64 v[76:79], v185 offset0:164 offset1:166
	ds_read2_b64 v[88:91], v185 offset0:168 offset1:170
	ds_read2_b64 v[214:217], v185 offset0:172 offset1:174
	s_waitcnt lgkmcnt(4)
	v_mfma_f32_32x32x16_bf16 v[32:47], v[92:95], v[64:67], v[32:47]
	v_mul_f32_e64 v62, v170, v62
	v_mul_f32_e64 v63, v170, v63
	v_mul_f32_e64 v60, v170, v60
	v_mul_f32_e64 v61, v170, v61
	v_mul_f32_e64 v58, v170, v58
	v_mul_f32_e64 v59, v170, v59
	v_pk_mul_f32 v[56:57], v[170:171], v[56:57] op_sel_hi:[0,1]
	v_pk_mul_f32 v[54:55], v[170:171], v[54:55] op_sel_hi:[0,1]
	v_pk_mul_f32 v[52:53], v[170:171], v[52:53] op_sel_hi:[0,1]
	v_pk_mul_f32 v[50:51], v[170:171], v[50:51] op_sel_hi:[0,1]
	v_pk_mul_f32 v[48:49], v[170:171], v[48:49] op_sel_hi:[0,1]
	v_cndmask_b32_e64 v212, 0, 1, s[12:13]
	s_waitcnt lgkmcnt(0)
	v_mfma_f32_32x32x16_bf16 v[48:63], v[72:75], v[84:87], v[48:63]
	s_barrier
; #define G_LOAD(ST, IT) do { const size_t o16 = (size_t)(IT) * 16384; \
;     _Pragma("unroll") for (int k = 0; k < 4; ++k) { ST[k] = *(const u32x4*)(gw + o16 + (tid + 256 * k) * 16); ST[4 + k] = *(const u32x4*)(gkt + o16 + (tid + 256 * k) * 16); } } while (0)
; #define U_LOAD(IT) do { _Pragma("unroll") for (int k = 0; k < 8; ++k) uc[k] = *(const uint2*)(gut + (size_t)(IT) * 8192 + dv * 64 + 32 * (k >> 2) + 8 * (k & 3) + 4 * hi); } while (0)
; __device__ __forceinline__ void gdn_scan_item(const Params& p, int bh, char* smem) {
;     ...
;   float sd_cur = gsd[bh * 128];
;   G_LOAD(sa, bh * 128); U_LOAD(bh * 128); G_WRITE(sa);
;   G_LOAD(sb_, bh * 128 + 1);
;   __syncthreads();
; #pragma unroll 1
;   for (int n2 = 0; n2 < 128; n2 += 2) {
;     SCAN_STEP(n2, sb_, sa);
;     SCAN_STEP(n2 + 1, sa, sb_);
	s_waitcnt vmcnt(32)
	ds_write2_b64 v171, v[128:129], v[130:131] offset1:1
	s_waitcnt vmcnt(31)
	ds_write2_b64 v199, v[132:133], v[134:135] offset1:1
	s_waitcnt vmcnt(30)
	ds_write2_b64 v200, v[136:137], v[138:139] offset1:1
	s_waitcnt vmcnt(29)
	ds_write2_b64 v201, v[140:141], v[142:143] offset1:1
	s_waitcnt vmcnt(28)
	ds_write2_b64 v202, v[144:145], v[146:147] offset1:1
	s_waitcnt vmcnt(27)
	ds_write2_b64 v203, v[148:149], v[150:151] offset1:1
	s_waitcnt vmcnt(26)
	ds_write2_b64 v204, v[152:153], v[154:155] offset1:1
	s_waitcnt vmcnt(25)
	ds_write2_b64 v205, v[156:157], v[158:159] offset1:1
	s_waitcnt lgkmcnt(0)
	s_barrier
	v_mfma_f32_32x32x16_bf16 v[48:63], v[76:79], v[80:83], v[48:63]
	s_cmpk_gt_u32 s16, 0x7c
	v_mfma_f32_32x32x16_bf16 v[48:63], v[88:91], v[68:71], v[48:63]
	v_lshlrev_b32_e32 v68, 2, v212
	global_load_dword v170, v68, s[6:7]
	v_mfma_f32_32x32x16_bf16 v[48:63], v[214:217], v[64:67], v[48:63]
	s_add_i32 s4, s0, s16
	s_add_i32 s4, s4, 3
	s_ashr_i32 s5, s4, 31
	s_lshl_b64 s[4:5], s[4:5], 14
	s_add_u32 s18, s2, s4
	s_addc_u32 s19, s3, s5
	s_add_u32 s4, s14, s4
	s_addc_u32 s5, s15, s5
	v_lshl_add_u64 v[64:65], s[18:19], 0, v[160:161]
	v_lshl_add_u64 v[66:67], s[4:5], 0, v[160:161]
	global_load_dwordx4 v[128:131], v[64:65], off
	global_load_dwordx4 v[132:135], v[66:67], off
	v_lshl_add_u64 v[64:65], s[18:19], 0, v[162:163]
	v_lshl_add_u64 v[66:67], s[4:5], 0, v[162:163]
	global_load_dwordx4 v[136:139], v[64:65], off
	global_load_dwordx4 v[140:143], v[66:67], off
	v_lshl_add_u64 v[64:65], s[18:19], 0, v[164:165]
	v_lshl_add_u64 v[66:67], s[4:5], 0, v[164:165]
	global_load_dwordx4 v[144:147], v[64:65], off
	global_load_dwordx4 v[148:151], v[66:67], off
	v_lshl_add_u64 v[64:65], s[18:19], 0, v[166:167]
	v_lshl_add_u64 v[66:67], s[4:5], 0, v[166:167]
	global_load_dwordx4 v[152:155], v[64:65], off
	global_load_dwordx4 v[156:159], v[66:67], off
.LBB0_1205:
	ds_read2_b64 v[64:67], v206 offset1:2
	ds_read2_b64 v[214:217], v206 offset0:4 offset1:6
	ds_read2_b64 v[68:71], v208 offset0:32 offset1:34
	ds_read2_b64 v[218:221], v208 offset0:36 offset1:38
	v_add_u32_e32 v238, 4, v184
	v_ashrrev_i32_e32 v239, 31, v238
	v_lshlrev_b64 v[230:231], 13, v[238:239]
	v_cvt_pk_bf16_f32 v222, v0, v1
	v_cvt_pk_bf16_f32 v223, v2, v3
	v_cvt_pk_bf16_f32 v224, v4, v5
	v_cvt_pk_bf16_f32 v225, v6, v7
	v_cvt_pk_bf16_f32 v226, v8, v9
	v_cvt_pk_bf16_f32 v227, v10, v11
	s_waitcnt lgkmcnt(3)
	v_mfma_f32_32x32x16_bf16 v[80:95], v[64:67], v[222:225], 0
	v_cvt_pk_bf16_f32 v228, v12, v13
	v_cvt_pk_bf16_f32 v229, v14, v15
	v_lshl_add_u64 v[240:241], v[178:179], 0, v[230:231]
	global_store_dwordx4 v[240:241], v[222:225], off
	global_store_dwordx4 v[240:241], v[226:229], off offset:1024
	s_waitcnt lgkmcnt(1)
	v_mfma_f32_32x32x16_bf16 v[64:79], v[68:71], v[222:225], 0
	v_mfma_f32_32x32x16_bf16 v[80:95], v[214:217], v[226:229], v[80:95]
	ds_read2_b64 v[214:217], v206 offset0:8 offset1:10
	ds_read2_b64 v[222:225], v206 offset0:12 offset1:14
	ds_read2_b64 v[230:233], v208 offset0:40 offset1:42
	ds_read2_b64 v[234:237], v208 offset0:44 offset1:46
	s_waitcnt lgkmcnt(4)
	v_mfma_f32_32x32x16_bf16 v[64:79], v[218:221], v[226:229], v[64:79]
	v_cvt_pk_bf16_f32 v218, v16, v17
	v_cvt_pk_bf16_f32 v219, v18, v19
	v_cvt_pk_bf16_f32 v220, v20, v21
	v_cvt_pk_bf16_f32 v221, v22, v23
	s_waitcnt lgkmcnt(3)
	s_nop 0
	v_mfma_f32_32x32x16_bf16 v[80:95], v[214:217], v[218:221], v[80:95]
	v_cvt_pk_bf16_f32 v214, v24, v25
	v_cvt_pk_bf16_f32 v215, v26, v27
	v_cvt_pk_bf16_f32 v216, v28, v29
	v_cvt_pk_bf16_f32 v217, v30, v31
	global_store_dwordx4 v[240:241], v[218:221], off offset:2048
	global_store_dwordx4 v[240:241], v[214:217], off offset:3072
	s_waitcnt lgkmcnt(1)
	v_mfma_f32_32x32x16_bf16 v[64:79], v[230:233], v[218:221], v[64:79]
	v_mfma_f32_32x32x16_bf16 v[80:95], v[222:225], v[214:217], v[80:95]
	ds_read2_b64 v[218:221], v206 offset0:16 offset1:18
	ds_read2_b64 v[222:225], v206 offset0:20 offset1:22
	ds_read2_b64 v[226:229], v208 offset0:48 offset1:50
	ds_read2_b64 v[230:233], v208 offset0:52 offset1:54
	s_waitcnt lgkmcnt(4)
	v_mfma_f32_32x32x16_bf16 v[64:79], v[234:237], v[214:217], v[64:79]
	v_cvt_pk_bf16_f32 v214, v32, v33
	v_cvt_pk_bf16_f32 v215, v34, v35
	v_cvt_pk_bf16_f32 v216, v36, v37
	v_cvt_pk_bf16_f32 v217, v38, v39
	v_add_co_u32_e32 v240, vcc, s1, v240
	s_waitcnt lgkmcnt(3)
	v_mfma_f32_32x32x16_bf16 v[80:95], v[218:221], v[214:217], v[80:95]
	v_cvt_pk_bf16_f32 v218, v40, v41
	v_cvt_pk_bf16_f32 v219, v42, v43
	v_cvt_pk_bf16_f32 v220, v44, v45
	v_cvt_pk_bf16_f32 v221, v46, v47
	v_addc_co_u32_e32 v241, vcc, 0, v241, vcc
	global_store_dwordx4 v[240:241], v[214:217], off
	global_store_dwordx4 v[240:241], v[218:221], off offset:1024
	s_waitcnt lgkmcnt(1)
	v_mfma_f32_32x32x16_bf16 v[64:79], v[226:229], v[214:217], v[64:79]
	v_mfma_f32_32x32x16_bf16 v[80:95], v[222:225], v[218:221], v[80:95]
	ds_read2_b64 v[214:217], v206 offset0:24 offset1:26
	ds_read2_b64 v[222:225], v206 offset0:28 offset1:30
	ds_read2_b64 v[226:229], v208 offset0:56 offset1:58
	ds_read2_b64 v[234:237], v208 offset0:60 offset1:62
	s_waitcnt lgkmcnt(4)
	v_mfma_f32_32x32x16_bf16 v[64:79], v[230:233], v[218:221], v[64:79]
	v_cvt_pk_bf16_f32 v218, v48, v49
	v_cvt_pk_bf16_f32 v219, v50, v51
	v_cvt_pk_bf16_f32 v220, v52, v53
	v_cvt_pk_bf16_f32 v221, v54, v55
	v_cvt_pk_bf16_f32 v230, v56, v57
	v_cvt_pk_bf16_f32 v231, v58, v59
	s_waitcnt lgkmcnt(3)
	v_mfma_f32_32x32x16_bf16 v[80:95], v[214:217], v[218:221], v[80:95]
	v_cvt_pk_bf16_f32 v232, v60, v61
	v_cvt_pk_bf16_f32 v233, v62, v63
	s_waitcnt vmcnt(22)
	v_permlane32_swap_b32_e32 v194, v196
	v_permlane32_swap_b32_e32 v195, v197
	v_lshlrev_b32_e32 v216, 16, v196
	v_and_b32_e32 v217, 0xffff0000, v196
	v_lshlrev_b64 v[214:215], 12, v[238:239]
	v_lshlrev_b32_e32 v238, 16, v197
	v_and_b32_e32 v239, 0xffff0000, v197
	s_waitcnt lgkmcnt(1)
	v_mfma_f32_32x32x16_bf16 v[64:79], v[226:229], v[218:221], v[64:79]
	s_waitcnt vmcnt(21)
	v_permlane32_swap_b32_e32 v190, v192
	v_permlane32_swap_b32_e32 v191, v193
	v_lshlrev_b32_e32 v208, 16, v191
	v_and_b32_e32 v213, 0xffff0000, v191
	v_lshl_add_u64 v[214:215], v[180:181], 0, v[214:215]
	v_cmp_ne_u32_e64 s[4:5], 1, v212
	s_andn2_b64 vcc, exec, s[12:13]
	global_store_dwordx4 v[240:241], v[218:221], off offset:2048
	global_store_dwordx4 v[240:241], v[230:233], off offset:3072
	v_mfma_f32_32x32x16_bf16 v[80:95], v[222:225], v[230:233], v[80:95]
	s_waitcnt lgkmcnt(0)
	v_mfma_f32_32x32x16_bf16 v[64:79], v[234:237], v[230:233], v[64:79]
	s_nop 9
	v_add_f32_e64 v80, v216, -v80
	v_add_f32_e64 v81, v217, -v81
	v_lshlrev_b32_e32 v216, 16, v194
	v_and_b32_e32 v217, 0xffff0000, v194
	v_add_f32_e64 v84, v216, -v84
	v_add_f32_e64 v85, v217, -v85
	v_lshlrev_b32_e32 v216, 16, v195
	v_and_b32_e32 v217, 0xffff0000, v195
	v_pk_add_f32 v[86:87], v[216:217], v[86:87] neg_lo:[0,1] neg_hi:[0,1]
	v_lshlrev_b32_e32 v216, 16, v192
	v_and_b32_e32 v217, 0xffff0000, v192
	v_pk_add_f32 v[82:83], v[238:239], v[82:83] neg_lo:[0,1] neg_hi:[0,1]
	v_pk_add_f32 v[88:89], v[216:217], v[88:89] neg_lo:[0,1] neg_hi:[0,1]
	v_cvt_pk_bf16_f32 v80, v80, v81
	v_cvt_pk_bf16_f32 v81, v82, v83
	v_cvt_pk_bf16_f32 v82, v84, v85
	v_cvt_pk_bf16_f32 v84, v88, v89
	s_waitcnt vmcnt(22)
	v_permlane32_swap_b32_e32 v250, v252
	v_permlane32_swap_b32_e32 v251, v253
	v_mov_b32_e32 v176, v250
	v_mov_b32_e32 v177, v251
	v_mov_b32_e32 v186, v252
	v_mov_b32_e32 v187, v253
	v_lshlrev_b32_e32 v88, 16, v186
	v_and_b32_e32 v89, 0xffff0000, v186
	v_pk_add_f32 v[64:65], v[88:89], v[64:65] neg_lo:[0,1] neg_hi:[0,1]
	v_lshlrev_b32_e32 v88, 16, v187
	v_and_b32_e32 v89, 0xffff0000, v187
	v_pk_add_f32 v[66:67], v[88:89], v[66:67] neg_lo:[0,1] neg_hi:[0,1]
	s_waitcnt vmcnt(22)
	v_lshlrev_b32_e32 v88, 16, v176
	v_and_b32_e32 v89, 0xffff0000, v176
	v_pk_add_f32 v[68:69], v[88:89], v[68:69] neg_lo:[0,1] neg_hi:[0,1]
	v_lshlrev_b32_e32 v88, 16, v177
	v_and_b32_e32 v89, 0xffff0000, v177
	v_pk_add_f32 v[70:71], v[88:89], v[70:71] neg_lo:[0,1] neg_hi:[0,1]
	s_waitcnt vmcnt(21)
	v_permlane32_swap_b32_e32 v172, v174
	v_permlane32_swap_b32_e32 v173, v175
	v_lshlrev_b32_e32 v88, 16, v174
	v_and_b32_e32 v89, 0xffff0000, v174
	v_pk_add_f32 v[72:73], v[88:89], v[72:73] neg_lo:[0,1] neg_hi:[0,1]
	v_lshlrev_b32_e32 v88, 16, v175
	v_and_b32_e32 v89, 0xffff0000, v175
	v_lshlrev_b32_e32 v216, 16, v193
	v_and_b32_e32 v217, 0xffff0000, v193
	v_pk_add_f32 v[74:75], v[88:89], v[74:75] neg_lo:[0,1] neg_hi:[0,1]
	s_waitcnt vmcnt(21)
	v_lshlrev_b32_e32 v88, 16, v172
	v_and_b32_e32 v89, 0xffff0000, v172
	v_pk_add_f32 v[90:91], v[216:217], v[90:91] neg_lo:[0,1] neg_hi:[0,1]
	v_lshlrev_b32_e32 v216, 16, v190
	v_and_b32_e32 v217, 0xffff0000, v190
	v_pk_add_f32 v[76:77], v[88:89], v[76:77] neg_lo:[0,1] neg_hi:[0,1]
	v_lshlrev_b32_e32 v88, 16, v173
	v_and_b32_e32 v89, 0xffff0000, v173
	s_add_i32 s98, s0, s16
	s_add_i32 s98, s98, 2
	s_ashr_i32 s99, s98, 31
	s_lshl_b64 s[98:99], s[98:99], 14
	v_lshl_add_u64 v[246:247], v[182:183], 0, s[98:99]
	v_lshl_add_u64 v[246:247], v[246:247], 0, v[254:255]
	global_load_dwordx4 v[194:197], v[246:247], off
	global_load_dwordx4 v[190:193], v[246:247], off offset:32
	global_load_dwordx4 v[250:253], v[246:247], off offset:64
	global_load_dwordx4 v[172:175], v[246:247], off offset:96
	v_pk_add_f32 v[92:93], v[216:217], v[92:93] neg_lo:[0,1] neg_hi:[0,1]
	v_sub_f32_e32 v95, v213, v95
	v_sub_f32_e32 v94, v208, v94
	v_sub_f32_e32 v79, v89, v79
	v_sub_f32_e32 v78, v88, v78
	v_cvt_pk_bf16_f32 v83, v86, v87
	v_cvt_pk_bf16_f32 v85, v90, v91
	v_cvt_pk_bf16_f32 v86, v92, v93
	v_cvt_pk_bf16_f32 v87, v94, v95
	v_cvt_pk_bf16_f32 v64, v64, v65
	v_cvt_pk_bf16_f32 v65, v66, v67
	v_cvt_pk_bf16_f32 v66, v68, v69
	v_cvt_pk_bf16_f32 v67, v70, v71
	v_cvt_pk_bf16_f32 v68, v72, v73
	v_cvt_pk_bf16_f32 v69, v74, v75
	v_cvt_pk_bf16_f32 v70, v76, v77
	v_cvt_pk_bf16_f32 v71, v78, v79
	global_store_dwordx4 v[214:215], v[80:83], off
	global_store_dwordx4 v[214:215], v[84:87], off offset:1024
	global_store_dwordx4 v[214:215], v[64:67], off offset:2048
	global_store_dwordx4 v[214:215], v[68:71], off offset:3072
